# P0b: the agent acquire behind the modulation-ready counter is dropped (the modulation rows were never in this CU's L1 and are published with write-through stores before the counter moves)
# speedup vs baseline: 1.0222x; 1.0049x over previous
.LBB0_61:
	global_load_dword v64, v69, s[46:47] sc1
	s_waitcnt vmcnt(0)
	v_readfirstlane_b32 s8, v64
	s_cmp_gt_u32 s8, 63
	s_mov_b64 s[8:9], -1
	s_cbranch_scc1 .LBB0_60
	s_add_i32 s12, s12, -1
	s_cmp_eq_u32 s12, 0
	s_cselect_b64 s[8:9], -1, 0
	s_sleep 2
	s_branch .LBB0_60
.LBB0_63:
	s_nop 0
.LBB0_64:
	s_waitcnt vmcnt(15)
	v_mul_f32_e32 v64, v61, v61
	v_mul_f32_e32 v65, v63, v63
	v_fmac_f32_e32 v64, v60, v60
	v_fmac_f32_e32 v65, v62, v62
	v_add_f32_e32 v64, v64, v65
	s_waitcnt vmcnt(7)
	v_mul_f32_e32 v65, v57, v57
	v_mul_f32_e32 v66, v59, v59
	v_fmac_f32_e32 v65, v56, v56
	v_fmac_f32_e32 v66, v58, v58
	v_add_f32_e32 v65, v65, v66
	v_mul_f32_e32 v66, v53, v53
	v_mul_f32_e32 v67, v55, v55
	v_fmac_f32_e32 v66, v52, v52
	v_fmac_f32_e32 v67, v54, v54
	v_add_f32_e32 v66, v66, v67
	v_add_f32_e32 v64, v64, v66
	s_waitcnt vmcnt(6)
	v_mul_f32_e32 v66, v49, v49
	v_mul_f32_e32 v67, v51, v51
	v_fmac_f32_e32 v66, v48, v48
	v_fmac_f32_e32 v67, v50, v50
	v_add_f32_e32 v66, v66, v67
	v_add_f32_e32 v65, v65, v66
	v_mul_f32_e32 v66, v45, v45
	v_mul_f32_e32 v67, v47, v47
	v_fmac_f32_e32 v66, v44, v44
	v_fmac_f32_e32 v67, v46, v46
	v_add_f32_e32 v66, v66, v67
	v_add_f32_e32 v64, v64, v66
	s_waitcnt vmcnt(5)
	v_mul_f32_e32 v66, v41, v41
	v_mul_f32_e32 v67, v43, v43
	v_fmac_f32_e32 v66, v40, v40
	v_fmac_f32_e32 v67, v42, v42
	v_add_f32_e32 v66, v66, v67
	v_add_f32_e32 v65, v65, v66
	v_mul_f32_e32 v66, v37, v37
	v_mul_f32_e32 v67, v39, v39
	v_fmac_f32_e32 v66, v36, v36
	v_fmac_f32_e32 v67, v38, v38
	v_add_f32_e32 v66, v66, v67
	v_add_f32_e32 v64, v64, v66
	s_waitcnt vmcnt(4)
	v_mul_f32_e32 v66, v33, v33
	v_mul_f32_e32 v67, v35, v35
	v_fmac_f32_e32 v66, v32, v32
	v_fmac_f32_e32 v67, v34, v34
	v_add_f32_e32 v66, v66, v67
	v_add_f32_e32 v65, v65, v66
	v_mul_f32_e32 v66, v29, v29
	v_mul_f32_e32 v67, v31, v31
	v_fmac_f32_e32 v66, v28, v28
	v_fmac_f32_e32 v67, v30, v30
	s_min_i32 s8, s38, 0x2000
	v_add_f32_e32 v66, v66, v67
	s_ashr_i32 s8, s8, 11
	s_min_i32 s5, s5, 0x2000
	v_add_f32_e32 v64, v64, v66
	s_waitcnt vmcnt(3)
	v_mul_f32_e32 v66, v25, v25
	v_mul_f32_e32 v67, v27, v27
	v_fmac_f32_e32 v66, v24, v24
	v_fmac_f32_e32 v67, v26, v26
	s_ashr_i32 s5, s5, 11
	s_mul_hi_i32 s9, s8, 0xc000
	s_mul_i32 s8, s8, 0xc000
	v_add_f32_e32 v66, v66, v67
	s_add_u32 s12, s42, s8
	v_add_f32_e32 v100, v65, v66
	v_mul_f32_e32 v65, v21, v21
	v_mul_f32_e32 v66, v23, v23
	s_addc_u32 s13, s43, s9
	s_mul_hi_i32 s9, s5, 0xc000
	s_mul_i32 s5, s5, 0xc000
	v_fmac_f32_e32 v65, v20, v20
	v_fmac_f32_e32 v66, v22, v22
	s_add_u32 s8, s42, s5
	v_add_f32_e32 v65, v65, v66
	s_addc_u32 s9, s43, s9
	v_add_f32_e32 v101, v64, v65
	s_waitcnt vmcnt(2)
	v_mul_f32_e32 v64, v17, v17
	v_mul_f32_e32 v65, v19, v19
	s_add_u32 s14, s12, 0x2000
	v_fmac_f32_e32 v64, v16, v16
	v_fmac_f32_e32 v65, v18, v18
	s_addc_u32 s15, s13, 0
	v_lshlrev_b32_e32 v68, 2, v70
	v_add_f32_e32 v102, v64, v65
	global_load_dwordx4 v[64:67], v[72:73], off
	global_load_dwordx4 v[104:107], v68, s[14:15]
	global_load_dwordx4 v[108:111], v68, s[12:13]
	v_add_f32_e32 v100, v100, v102
	v_mul_f32_e32 v102, v13, v13
	v_mul_f32_e32 v103, v15, v15
	v_fmac_f32_e32 v102, v12, v12
	v_fmac_f32_e32 v103, v14, v14
	v_add_f32_e32 v102, v102, v103
	v_add_f32_e32 v101, v101, v102
	s_waitcnt vmcnt(4)
	v_mul_f32_e32 v102, v9, v9
	v_mul_f32_e32 v103, v11, v11
	v_fmac_f32_e32 v102, v8, v8
	v_fmac_f32_e32 v103, v10, v10
	v_add_f32_e32 v102, v102, v103
	v_add_f32_e32 v100, v100, v102
	v_mul_f32_e32 v102, v5, v5
	v_mul_f32_e32 v103, v7, v7
	v_fmac_f32_e32 v102, v4, v4
	v_fmac_f32_e32 v103, v6, v6
	v_add_f32_e32 v102, v102, v103
	v_add_f32_e32 v101, v101, v102
	s_waitcnt vmcnt(3)
	v_mul_f32_e32 v102, v1, v1
	v_mul_f32_e32 v103, v3, v3
	v_fmac_f32_e32 v102, v0, v0
	v_fmac_f32_e32 v103, v2, v2
	v_add_f32_e32 v102, v102, v103
	ds_bpermute_b32 v103, v75, v101
	v_add_f32_e32 v100, v100, v102
	ds_bpermute_b32 v102, v75, v100
	s_lshl_b64 s[34:35], s[38:39], 12
	s_add_u32 s18, s8, 0x2000
	s_waitcnt lgkmcnt(1)
	v_add_f32_e32 v101, v101, v103
	ds_bpermute_b32 v103, v77, v101
	s_waitcnt lgkmcnt(1)
	v_add_f32_e32 v100, v100, v102
	ds_bpermute_b32 v102, v77, v100
	s_addc_u32 s19, s9, 0
	s_ashr_i32 s5, s4, 31
	s_waitcnt lgkmcnt(1)
	v_add_f32_e32 v101, v101, v103
	ds_bpermute_b32 v103, v79, v101
	s_waitcnt lgkmcnt(1)
	v_add_f32_e32 v100, v100, v102
	ds_bpermute_b32 v102, v79, v100
	s_lshl_b64 s[4:5], s[4:5], 12
	s_add_u32 s16, s66, s4
	s_waitcnt lgkmcnt(1)
	v_add_f32_e32 v101, v101, v103
	ds_bpermute_b32 v103, v81, v101
	s_waitcnt lgkmcnt(1)
	v_add_f32_e32 v100, v100, v102
	ds_bpermute_b32 v102, v81, v100
	s_addc_u32 s17, s67, s5
	s_andn2_b64 vcc, exec, s[20:21]
	s_waitcnt lgkmcnt(1)
	v_add_f32_e32 v101, v101, v103
	ds_bpermute_b32 v103, v85, v101
	s_waitcnt lgkmcnt(1)
	v_add_f32_e32 v100, v100, v102
	ds_bpermute_b32 v102, v85, v100
	s_waitcnt lgkmcnt(1)
	v_add_f32_e32 v101, v101, v103
	ds_bpermute_b32 v103, v89, v101
	s_waitcnt lgkmcnt(1)
	v_add_f32_e32 v100, v100, v102
	ds_bpermute_b32 v102, v89, v100
	s_waitcnt lgkmcnt(1)
	v_add_f32_e32 v101, v101, v103
	v_fmamk_f32 v101, v101, 0x3a000000, v93
	s_waitcnt lgkmcnt(0)
	v_add_f32_e32 v100, v100, v102
	v_rsq_f32_e32 v102, v101
	v_fmamk_f32 v100, v100, 0x3a000000, v93
	v_rsq_f32_e32 v100, v100
	v_pk_mul_f32 v[62:63], v[102:103], v[62:63] op_sel_hi:[0,1]
	v_pk_mul_f32 v[60:61], v[102:103], v[60:61] op_sel_hi:[0,1]
	v_mov_b32_e32 v101, v100
	s_waitcnt vmcnt(2)
	v_pk_mul_f32 v[60:61], v[64:65], v[60:61]
	v_pk_mul_f32 v[62:63], v[66:67], v[62:63]
	s_waitcnt vmcnt(1)
	v_pk_add_f32 v[106:107], v[106:107], 1.0 op_sel_hi:[1,0]
	v_pk_add_f32 v[104:105], v[104:105], 1.0 op_sel_hi:[1,0]
	s_waitcnt vmcnt(0)
	v_pk_fma_f32 v[62:63], v[62:63], v[106:107], v[110:111]
	v_pk_fma_f32 v[60:61], v[60:61], v[104:105], v[108:109]
	v_cvt_pk_bf16_f32 v105, v62, v63
	v_cvt_pk_bf16_f32 v104, v60, v61
	v_lshl_add_u64 v[60:61], v[96:97], 0, s[34:35]
	v_cndmask_b32_e64 v62, 0, 1, s[20:21]
	global_store_dwordx2 v[60:61], v[104:105], off
	v_cmp_ne_u32_e64 s[4:5], 1, v62
	v_lshlrev_b32_e32 v104, 1, v70
	s_cbranch_vccnz .LBB0_66
	global_load_dwordx4 v[106:109], v68, s[18:19]
	global_load_dwordx4 v[110:113], v68, s[8:9]
	v_mov_b32_e32 v62, v100
	v_mov_b32_e32 v63, v100
	v_pk_mul_f32 v[56:57], v[100:101], v[56:57]
	v_pk_mul_f32 v[58:59], v[62:63], v[58:59]
	v_pk_mul_f32 v[56:57], v[64:65], v[56:57]
	v_pk_mul_f32 v[58:59], v[66:67], v[58:59]
	s_waitcnt vmcnt(1)
	v_pk_add_f32 v[62:63], v[108:109], 1.0 op_sel_hi:[1,0]
	v_pk_add_f32 v[64:65], v[106:107], 1.0 op_sel_hi:[1,0]
	s_waitcnt vmcnt(0)
	v_pk_fma_f32 v[58:59], v[58:59], v[62:63], v[112:113]
	v_pk_fma_f32 v[56:57], v[56:57], v[64:65], v[110:111]
	s_nop 0
	v_cvt_pk_bf16_f32 v56, v56, v57
	v_cvt_pk_bf16_f32 v57, v58, v59
	global_store_dwordx2 v104, v[56:57], s[16:17]
